# v45: NA attention key rows walked in rotated order (row mod 8 == step) so workgroups sharing a K/V row fetch it at the same step (v41 + NA rotation)
# speedup vs baseline: 1.0022x; 1.0010x over previous
.LBB0_282:
	s_or_b64 exec, exec, s[2:3]
	s_max_u32 s99, s39, 4
	s_min_u32 s99, s99, 0x7c
	s_sub_u32 s99, 4, s99
	s_and_b32 s99, s99, 7
	s_mul_i32 s98, s99, 0x7c
	v_med3_u32 v1, s39, 4, v241
	v_lshlrev_b32_e32 v2, 4, v0
	v_lshlrev_b32_e32 v1, 6, v1
	v_and_b32_e32 v200, 0x70, v2
	v_add_u32_e32 v2, 0xffffff00, v1
	v_ashrrev_i32_e32 v10, 3, v0
	v_add_u32_e32 v1, s17, v2
	v_add_u32_e32 v6, v1, v10
	v_ashrrev_i32_e32 v7, 31, v6
	v_lshlrev_b64 v[6:7], 12, v[6:7]
	v_lshl_add_u64 v[6:7], s[18:19], 0, v[6:7]
	s_lshl_b32 s2, s38, 1
	s_mov_b32 s3, s71
	s_lshl_b32 s6, s37, 10
	v_lshl_add_u64 v[6:7], v[6:7], 0, s[2:3]
	s_lshl_b32 s13, s99, 18
	v_add_co_u32_e32 v6, vcc, s13, v6
	v_addc_co_u32_e32 v7, vcc, 0, v7, vcc
	s_or_b32 s2, s6, s38
	v_add_u32_e32 v8, s2, v10
	v_ashrrev_i32_e32 v9, 31, v8
	v_lshlrev_b64 v[8:9], 14, v[8:9]
	v_lshl_add_u64 v[8:9], s[68:69], 0, v[8:9]
	v_mov_b32_e32 v3, v201
	v_lshl_add_u64 v[2:3], v[2:3], 1, v[8:9]
	v_lshl_add_u64 v[2:3], v[2:3], 0, v[200:201]
	s_lshl_b32 s13, s99, 7
	v_add_co_u32_e32 v2, vcc, s13, v2
	v_addc_co_u32_e32 v3, vcc, 0, v3, vcc
	v_add_co_u32_e32 v8, vcc, s72, v2
	s_mov_b32 s2, 0x200000
	s_nop 0
	v_addc_co_u32_e32 v9, vcc, 0, v3, vcc
	global_load_dwordx4 v[112:115], v[2:3], off
	global_load_dwordx4 v[116:119], v[8:9], off
	v_add_co_u32_e32 v8, vcc, s2, v2
	s_mov_b32 s2, 0x300000
	s_nop 0
	v_addc_co_u32_e32 v9, vcc, 0, v3, vcc
	v_add_co_u32_e32 v2, vcc, s2, v2
	v_lshl_add_u64 v[6:7], v[6:7], 0, v[200:201]
	s_nop 0
	v_addc_co_u32_e32 v3, vcc, 0, v3, vcc
	global_load_dwordx4 v[132:135], v[8:9], off
	global_load_dwordx4 v[140:143], v[2:3], off
	global_load_dwordx4 v[120:123], v[6:7], off offset:2048
	global_load_dwordx4 v[124:127], v[6:7], off offset:2176
	global_load_dwordx4 v[128:131], v[6:7], off offset:2304
	global_load_dwordx4 v[136:139], v[6:7], off offset:2432
	v_and_b32_e32 v3, 31, v0
	v_and_b32_e32 v2, 19, v0
	v_lshrrev_b32_e32 v0, 1, v0
	v_mul_lo_u32 v6, v10, s24
	v_lshlrev_b32_e32 v7, 1, v3
	s_waitcnt vmcnt(30)
	v_lshlrev_b32_e32 v148, 3, v5
	v_med3_i32 v5, v4, 8, 56
	v_and_b32_e32 v0, 4, v0
	v_add3_u32 v147, v6, v200, 0
	v_and_b32_e32 v6, 8, v7
	v_sub_u32_e32 v5, v148, v5
	v_or3_b32 v2, v2, v6, v0
	v_mul_u32_u24_e32 v149, 0x90, v2
	v_add_u32_e32 v2, 10, v5
	v_cmp_gt_u32_e64 s[52:53], 16, v2
	v_add_u32_e32 v2, 11, v5
	v_cmp_gt_u32_e64 s[54:55], 16, v2
	v_add_u32_e32 v2, 12, v5
	v_cmp_gt_u32_e64 s[56:57], 16, v2
	v_add_u32_e32 v2, 13, v5
	v_cmp_gt_u32_e64 s[58:59], 16, v2
	v_add_u32_e32 v2, 14, v5
	v_cmp_gt_u32_e64 s[60:61], 16, v2
	v_add_u32_e32 v2, 15, v5
	v_cmp_gt_u32_e64 s[62:63], 16, v2
	v_add_u32_e32 v2, 25, v5
	v_add_u32_e32 v6, 41, v5
	v_cmp_gt_u32_e64 s[66:67], 16, v2
	v_add_u32_e32 v2, 26, v5
	v_cmp_gt_u32_e64 s[82:83], 16, v6
	v_add_u32_e32 v6, 42, v5
	s_mov_b64 s[14:15], s[68:69]
	v_cmp_gt_u32_e64 s[68:69], 16, v2
	v_add_u32_e32 v2, 27, v5
	v_cmp_gt_u32_e64 s[84:85], 16, v6
	v_add_u32_e32 v6, 43, v5
	s_mov_b64 s[0:1], s[70:71]
	s_lshr_b32 s2, s47, 2
	v_cmp_gt_u32_e64 s[70:71], 16, v2
	v_add_u32_e32 v2, 28, v5
	v_cmp_gt_u32_e64 s[86:87], 16, v6
	v_add_u32_e32 v6, 44, v5
	s_and_b32 s35, s2, 0x7f
	v_cmp_gt_u32_e64 s[72:73], 16, v2
	v_add_u32_e32 v2, 29, v5
	v_cmp_gt_u32_e64 s[88:89], 16, v6
	v_add_u32_e32 v6, 45, v5
	v_sub_u32_e32 v4, v148, v4
	v_med3_u32 v8, s35, 4, v241
	v_cmp_gt_u32_e64 s[74:75], 16, v2
	v_add_u32_e32 v2, 30, v5
	v_cmp_gt_u32_e64 s[90:91], 16, v6
	v_add_u32_e32 v6, 46, v5
	s_mul_i32 s3, s36, 0x4800
	v_add_u32_e32 v7, 8, v5
	v_add_u32_e32 v4, 15, v4
	v_add_u32_e32 v9, 9, v5
	s_movk_i32 s2, 0x7c
	v_lshlrev_b32_e32 v12, 7, v8
	s_movk_i32 s4, 0xffef
	v_cmp_gt_u32_e64 s[76:77], 16, v2
	v_add_u32_e32 v2, 31, v5
	v_cmp_gt_u32_e64 s[92:93], 16, v6
	v_add_u32_e32 v6, 47, v5
	s_add_i32 s37, s3, 0
	v_mul_lo_u32 v11, v8, s2
	v_cmp_gt_u32_e64 s[2:3], 16, v7
	v_add_u32_e32 v0, 0xfffffe00, v12
	v_cmp_gt_u32_e64 s[48:49], 16, v9
	v_cmp_lt_u32_e64 s[64:65], s4, v7
	v_cmp_gt_u32_e64 s[78:79], 16, v2
	v_and_b32_e32 v2, -16, v7
	s_movk_i32 s4, 0xffe0
	v_cmp_gt_u32_e64 s[94:95], 16, v6
	v_med3_i32 v6, v4, 0, 30
	v_max_i32_e32 v7, -1, v4
	v_max_i32_e32 v9, -2, v4
	v_max_i32_e32 v12, -3, v4
	v_max_i32_e32 v13, -4, v4
	v_max_i32_e32 v14, -5, v4
	v_max_i32_e32 v15, -6, v4
	v_max_i32_e32 v16, -7, v4
	v_max_i32_e32 v17, -16, v4
	v_max_i32_e32 v18, 0xffffffef, v4
	v_max_i32_e32 v19, 0xffffffee, v4
	v_max_i32_e32 v20, 0xffffffed, v4
	v_max_i32_e32 v21, 0xffffffec, v4
	v_max_i32_e32 v22, 0xffffffeb, v4
	v_max_i32_e32 v23, 0xffffffea, v4
	v_max_i32_e32 v24, 0xffffffe9, v4
	v_max_i32_e32 v25, 0xffffffe0, v4
	v_max_i32_e32 v26, 0xffffffdf, v4
	v_max_i32_e32 v27, 0xffffffde, v4
	v_max_i32_e32 v28, 0xffffffdd, v4
	v_max_i32_e32 v29, 0xffffffdc, v4
	v_max_i32_e32 v30, 0xffffffdb, v4
	v_max_i32_e32 v31, 0xffffffda, v4
	v_max_i32_e32 v32, 0xffffffd9, v4
	v_max_i32_e32 v33, 0xffffffd0, v4
	v_max_i32_e32 v34, 0xffffffcf, v4
	v_max_i32_e32 v35, 0xffffffce, v4
	v_max_i32_e32 v36, 0xffffffcd, v4
	v_max_i32_e32 v37, 0xffffffcc, v4
	v_max_i32_e32 v38, 0xffffffcb, v4
	v_max_i32_e32 v39, 0xffffffca, v4
	v_max_i32_e32 v4, 0xffffffc9, v4
	v_cmp_eq_u32_e64 s[80:81], s4, v2
	s_movk_i32 s4, 0xffd0
	v_add_u32_e32 v4, 55, v4
	s_mulk_i32 s36, 0x744
	v_cmp_eq_u32_e64 s[96:97], s4, v2
	v_add_u32_e32 v2, 57, v5
	v_add_u32_e32 v7, 1, v7
	v_add_u32_e32 v9, 2, v9
	v_add_u32_e32 v12, 3, v12
	v_add_u32_e32 v13, 4, v13
	v_add_u32_e32 v14, 5, v14
	v_add_u32_e32 v15, 6, v15
	v_add_u32_e32 v16, 7, v16
	v_add_u32_e32 v17, 16, v17
	v_add_u32_e32 v18, 17, v18
	v_add_u32_e32 v19, 18, v19
	v_add_u32_e32 v20, 19, v20
	v_add_u32_e32 v21, 20, v21
	v_add_u32_e32 v22, 21, v22
	v_add_u32_e32 v23, 22, v23
	v_add_u32_e32 v24, 23, v24
	v_add_u32_e32 v25, 32, v25
	v_add_u32_e32 v26, 33, v26
	v_add_u32_e32 v27, 34, v27
	v_add_u32_e32 v28, 35, v28
	v_add_u32_e32 v29, 36, v29
	v_add_u32_e32 v30, 37, v30
	v_add_u32_e32 v31, 38, v31
	v_add_u32_e32 v32, 39, v32
	v_add_u32_e32 v33, 48, v33
	v_add_u32_e32 v34, 49, v34
	v_add_u32_e32 v35, 50, v35
	v_add_u32_e32 v36, 51, v36
	v_add_u32_e32 v37, 52, v37
	v_add_u32_e32 v38, 53, v38
	v_add_u32_e32 v39, 54, v39
	v_min_u32_e32 v4, 30, v4
	v_add_u32_e32 v11, s36, v11
	s_mulk_i32 s35, 0x7c
	v_cmp_gt_u32_e64 s[40:41], 16, v2
	v_add_u32_e32 v2, 58, v5
	v_min_u32_e32 v7, 30, v7
	v_min_u32_e32 v9, 30, v9
	v_min_u32_e32 v12, 30, v12
	v_min_u32_e32 v13, 30, v13
	v_min_u32_e32 v14, 30, v14
	v_min_u32_e32 v15, 30, v15
	v_min_u32_e32 v16, 30, v16
	v_min_u32_e32 v17, 30, v17
	v_min_u32_e32 v18, 30, v18
	v_min_u32_e32 v19, 30, v19
	v_min_u32_e32 v20, 30, v20
	v_min_u32_e32 v21, 30, v21
	v_min_u32_e32 v22, 30, v22
	v_min_u32_e32 v23, 30, v23
	v_min_u32_e32 v24, 30, v24
	v_min_u32_e32 v25, 30, v25
	v_min_u32_e32 v26, 30, v26
	v_min_u32_e32 v27, 30, v27
	v_min_u32_e32 v28, 30, v28
	v_min_u32_e32 v29, 30, v29
	v_min_u32_e32 v30, 30, v30
	v_min_u32_e32 v31, 30, v31
	v_min_u32_e32 v32, 30, v32
	v_min_u32_e32 v33, 30, v33
	v_min_u32_e32 v34, 30, v34
	v_min_u32_e32 v35, 30, v35
	v_min_u32_e32 v36, 30, v36
	v_min_u32_e32 v37, 30, v37
	v_min_u32_e32 v38, 30, v38
	v_min_u32_e32 v39, 30, v39
	v_lshl_add_u32 v4, v4, 2, v11
	v_lshlrev_b32_e32 v8, 6, v8
	v_cmp_gt_u32_e64 s[38:39], 16, v2
	v_add_u32_e32 v2, 59, v5
	v_lshl_add_u32 v6, v6, 2, v11
	v_lshl_add_u32 v7, v7, 2, v11
	v_lshl_add_u32 v9, v9, 2, v11
	v_lshl_add_u32 v12, v12, 2, v11
	v_lshl_add_u32 v13, v13, 2, v11
	v_lshl_add_u32 v14, v14, 2, v11
	v_lshl_add_u32 v15, v15, 2, v11
	v_lshl_add_u32 v16, v16, 2, v11
	v_lshl_add_u32 v17, v17, 2, v11
	v_lshl_add_u32 v18, v18, 2, v11
	v_lshl_add_u32 v19, v19, 2, v11
	v_lshl_add_u32 v20, v20, 2, v11
	v_lshl_add_u32 v21, v21, 2, v11
	v_lshl_add_u32 v22, v22, 2, v11
	v_lshl_add_u32 v23, v23, 2, v11
	v_lshl_add_u32 v24, v24, 2, v11
	v_lshl_add_u32 v25, v25, 2, v11
	v_lshl_add_u32 v26, v26, 2, v11
	v_lshl_add_u32 v27, v27, 2, v11
	v_lshl_add_u32 v28, v28, 2, v11
	v_lshl_add_u32 v29, v29, 2, v11
	v_lshl_add_u32 v30, v30, 2, v11
	v_lshl_add_u32 v31, v31, 2, v11
	v_lshl_add_u32 v32, v32, 2, v11
	v_lshl_add_u32 v33, v33, 2, v11
	v_lshl_add_u32 v34, v34, 2, v11
	v_lshl_add_u32 v35, v35, 2, v11
	v_lshl_add_u32 v36, v36, 2, v11
	v_lshl_add_u32 v37, v37, 2, v11
	v_lshl_add_u32 v38, v38, 2, v11
	v_lshl_add_u32 v39, v39, 2, v11
	v_subrev_u32_e32 v11, s35, v4
	v_add_u32_e32 v4, 62, v5
	s_lshl_b32 s34, s16, 8
	v_cmp_gt_u32_e64 s[44:45], 16, v2
	v_add_u32_e32 v2, 60, v5
	v_cmp_gt_u32_e64 s[50:51], 16, v4
	v_add_u32_e32 v4, s17, v8
	v_cmp_gt_u32_e64 s[4:5], 16, v2
	v_add_u32_e32 v2, 61, v5
	s_or_b32 s6, s34, s6
	v_add_u32_e32 v4, v10, v4
	s_lshl_b32 s7, s16, 9
	v_cmp_gt_u32_e64 s[42:43], 16, v2
	v_add_u32_e32 v2, s6, v10
	v_add_u32_e32 v4, 0xffffff00, v4
	v_readlane_b32 s6, v254, 49
	v_add_u32_e32 v40, 63, v5
	v_ashrrev_i32_e32 v5, 31, v4
	s_add_u32 s6, s6, s7
	v_readlane_b32 s7, v254, 50
	v_mov_b32_e32 v1, v201
	v_subrev_u32_e32 v32, s35, v32
	v_subrev_u32_e32 v33, s35, v33
	v_subrev_u32_e32 v34, s35, v34
	v_subrev_u32_e32 v35, s35, v35
	v_subrev_u32_e32 v36, s35, v36
	v_subrev_u32_e32 v37, s35, v37
	v_subrev_u32_e32 v38, s35, v38
	v_subrev_u32_e32 v39, s35, v39
	v_lshlrev_b64 v[4:5], 12, v[4:5]
	s_addc_u32 s7, s7, 0
	s_waitcnt vmcnt(29)
	v_mul_u32_u24_e32 v154, 0x90, v3
	v_ashrrev_i32_e32 v3, 31, v2
	v_mov_b32_e32 v46, v201
	v_mov_b32_e32 v47, v201
	v_subrev_u32_e32 v6, s35, v6
	v_subrev_u32_e32 v7, s35, v7
	v_subrev_u32_e32 v9, s35, v9
	v_subrev_u32_e32 v12, s35, v12
	v_subrev_u32_e32 v13, s35, v13
	v_subrev_u32_e32 v14, s35, v14
	v_subrev_u32_e32 v15, s35, v15
	v_subrev_u32_e32 v16, s35, v16
	v_subrev_u32_e32 v17, s35, v17
	v_subrev_u32_e32 v18, s35, v18
	v_subrev_u32_e32 v19, s35, v19
	v_subrev_u32_e32 v20, s35, v20
	v_subrev_u32_e32 v21, s35, v21
	v_subrev_u32_e32 v22, s35, v22
	v_subrev_u32_e32 v23, s35, v23
	v_subrev_u32_e32 v24, s35, v24
	v_subrev_u32_e32 v25, s35, v25
	v_subrev_u32_e32 v26, s35, v26
	v_subrev_u32_e32 v27, s35, v27
	v_subrev_u32_e32 v28, s35, v28
	v_subrev_u32_e32 v29, s35, v29
	v_subrev_u32_e32 v30, s35, v30
	v_subrev_u32_e32 v31, s35, v31
	v_lshl_add_u64 v[150:151], s[6:7], 0, v[4:5]
	v_cmp_gt_u32_e64 s[6:7], 16, v40
	v_add_u32_e32 v178, s23, v32
	v_add_u32_e32 v179, s23, v33
	v_add_u32_e32 v180, s23, v34
	v_add_u32_e32 v181, s23, v35
	v_add_u32_e32 v182, s23, v36
	v_add_u32_e32 v183, s23, v37
	v_add_u32_e32 v184, s23, v38
	v_add_u32_e32 v185, s23, v39
	v_lshlrev_b64 v[2:3], 14, v[2:3]
	v_lshl_add_u64 v[0:1], s[10:11], 0, v[0:1]
	v_mov_b32_e32 v32, v201
	v_mov_b32_e32 v33, v201
	v_mov_b32_e32 v34, v201
	v_mov_b32_e32 v35, v201
	v_mov_b32_e32 v36, v201
	v_mov_b32_e32 v37, v201
	v_mov_b32_e32 v38, v201
	v_mov_b32_e32 v39, v201
	v_mov_b32_e32 v40, v201
	v_mov_b32_e32 v41, v201
	v_mov_b32_e32 v42, v201
	v_mov_b32_e32 v43, v201
	v_mov_b32_e32 v44, v201
	v_mov_b32_e32 v45, v201
	v_mov_b32_e32 v187, 0
	v_mov_b64_e32 v[62:63], v[46:47]
	s_mov_b32 s16, 0
	v_add_u32_e32 v155, s23, v6
	s_waitcnt vmcnt(28)
	v_add_u32_e32 v156, s23, v7
	v_add_u32_e32 v157, s23, v9
	v_add_u32_e32 v158, s23, v12
	v_add_u32_e32 v159, s23, v13
	v_add_u32_e32 v160, s23, v14
	v_add_u32_e32 v161, s23, v15
	v_add_u32_e32 v162, s23, v16
	v_add_u32_e32 v163, s23, v17
	v_add_u32_e32 v164, s23, v18
	v_add_u32_e32 v165, s23, v19
	v_add_u32_e32 v166, s23, v20
	v_add_u32_e32 v167, s23, v21
	v_add_u32_e32 v168, s23, v22
	v_add_u32_e32 v169, s23, v23
	v_add_u32_e32 v170, s23, v24
	v_add_u32_e32 v171, s23, v25
	v_add_u32_e32 v172, s23, v26
	v_add_u32_e32 v173, s23, v27
	v_add_u32_e32 v174, s23, v28
	v_add_u32_e32 v175, s23, v29
	v_add_u32_e32 v176, s23, v30
	v_add_u32_e32 v177, s23, v31
	v_add_u32_e32 v186, s23, v11
	v_lshl_add_u64 v[152:153], v[0:1], 0, v[2:3]
	v_mov_b64_e32 v[60:61], v[44:45]
	v_mov_b64_e32 v[58:59], v[42:43]
	v_mov_b64_e32 v[56:57], v[40:41]
	v_mov_b64_e32 v[54:55], v[38:39]
	v_mov_b64_e32 v[52:53], v[36:37]
	v_mov_b64_e32 v[50:51], v[34:35]
	v_mov_b64_e32 v[48:49], v[32:33]
	v_mov_b32_e32 v188, 0
	v_mov_b32_e32 v64, 0
	v_mov_b32_e32 v65, v187
	v_mov_b32_e32 v66, v187
	v_mov_b32_e32 v67, v187
	v_mov_b32_e32 v68, v187
	v_mov_b32_e32 v69, v187
	v_mov_b32_e32 v70, v187
	v_mov_b32_e32 v71, v187
	v_mov_b32_e32 v72, v187
	v_mov_b32_e32 v73, v187
	v_mov_b32_e32 v74, v187
	v_mov_b32_e32 v75, v187
	v_mov_b32_e32 v76, v187
	v_mov_b32_e32 v77, v187
	v_mov_b32_e32 v78, v187
	v_mov_b32_e32 v79, v187
	s_mov_b32 s36, 0
	s_add_i32 s99, s99, 1
	s_and_b32 s99, s99, 7
	s_lshl_b32 s13, s99, 18
	v_add_co_u32_e32 v150, vcc, s13, v150
	v_addc_co_u32_e32 v151, vcc, 0, v151, vcc
	v_add_co_u32_e32 v150, vcc, 0xfffc0000, v150
	v_addc_co_u32_e32 v151, vcc, -1, v151, vcc
	s_lshl_b32 s13, s99, 7
	v_add_co_u32_e32 v152, vcc, s13, v152
	v_addc_co_u32_e32 v153, vcc, 0, v153, vcc
	v_add_co_u32_e32 v152, vcc, 0xffffff80, v152
	v_addc_co_u32_e32 v153, vcc, -1, v153, vcc
	s_waitcnt vmcnt(7)
	ds_write_b128 v147, v[112:115] offset:9216
	s_waitcnt vmcnt(6)
	ds_write_b128 v147, v[116:119] offset:27648
	s_waitcnt vmcnt(5)
	ds_write_b128 v147, v[132:135] offset:46080
	s_waitcnt vmcnt(4)
	ds_write_b128 v147, v[140:143] offset:64512
	s_waitcnt vmcnt(3)
	ds_write_b128 v147, v[120:123]
	s_waitcnt vmcnt(2)
	ds_write_b128 v147, v[124:127] offset:18432
	s_waitcnt vmcnt(1)
	ds_write_b128 v147, v[128:131] offset:36864
	s_waitcnt vmcnt(0)
	ds_write_b128 v147, v[136:139] offset:55296
	s_waitcnt lgkmcnt(0)
	s_barrier
	s_branch .LBB0_284
.LBB0_283:
	s_addk_i32 s98, 0x7c
	s_cmpk_lg_i32 s98, 0x3e0
	s_cbranch_scc1 .Lna_rot_a
	s_mov_b32 s98, 0
.Lna_rot_a:
	s_cmpk_lg_i32 s98, 0x364
	s_cbranch_scc1 .Lna_rot_b
	v_add_co_u32_e32 v152, vcc, 0xfffffc00, v152
	v_addc_co_u32_e32 v153, vcc, -1, v153, vcc
	v_add_co_u32_e32 v150, vcc, 0xffe00000, v150
	v_addc_co_u32_e32 v151, vcc, -1, v151, vcc

.LBB0_286:
	s_bitcmp1_b32 s36, 0
	s_cselect_b32 s12, 0x12000, 0
	s_add_i32 s17, s37, s12
	v_add3_u32 v0, s17, v146, v149
	ds_read_b128 v[18:21], v0
	ds_read_b128 v[22:25], v0 offset:32
	v_mov_b64_e32 v[94:95], v[78:79]
	v_mov_b64_e32 v[92:93], v[76:77]
	v_mov_b64_e32 v[90:91], v[74:75]
	s_waitcnt lgkmcnt(1)
	v_mfma_f32_32x32x16_bf16 v[2:17], v[18:21], v[96:99], v[64:79]
	ds_read_b128 v[18:21], v0 offset:64
	v_mov_b64_e32 v[88:89], v[72:73]
	v_mov_b64_e32 v[86:87], v[70:71]
	v_mov_b64_e32 v[84:85], v[68:69]
	v_mov_b64_e32 v[82:83], v[66:67]
	v_mov_b64_e32 v[80:81], v[64:65]
	v_mov_b32_e32 v1, 0xf149f2ca
	s_waitcnt lgkmcnt(1)
	v_mfma_f32_32x32x16_bf16 v[2:17], v[22:25], v[100:103], v[2:17]
	s_waitcnt lgkmcnt(0)
	v_mfma_f32_32x32x16_bf16 v[2:17], v[18:21], v[104:107], v[2:17]
	ds_read_b128 v[18:21], v0 offset:96
	s_waitcnt lgkmcnt(0)
	v_mfma_f32_32x32x16_bf16 v[2:17], v[18:21], v[108:111], v[2:17]
	ds_read_b128 v[18:21], v0 offset:4608
	s_waitcnt lgkmcnt(0)
	v_mfma_f32_32x32x16_bf16 v[80:95], v[18:21], v[96:99], v[80:95]
	ds_read_b128 v[18:21], v0 offset:4640
	s_waitcnt lgkmcnt(0)
	v_mfma_f32_32x32x16_bf16 v[80:95], v[18:21], v[100:103], v[80:95]
	ds_read_b128 v[18:21], v0 offset:4672
	s_waitcnt lgkmcnt(0)
	v_mfma_f32_32x32x16_bf16 v[80:95], v[18:21], v[104:107], v[80:95]
	ds_read_b128 v[18:21], v0 offset:4704
	v_mov_b32_e32 v0, 0xf149f2ca
	s_waitcnt lgkmcnt(0)
	v_mfma_f32_32x32x16_bf16 v[80:95], v[18:21], v[108:111], v[80:95]
	v_mov_b32_e32 v203, 0xf149f2ca
	v_add_u32_e32 v189, s98, v155
	ds_read_b32 v189, v189
	v_add_u32_e32 v190, s98, v156
	ds_read_b32 v190, v190
	v_add_u32_e32 v191, s98, v157
	ds_read_b32 v191, v191
	v_add_u32_e32 v192, s98, v158
	ds_read_b32 v192, v192
	v_add_u32_e32 v193, s98, v159
	ds_read_b32 v193, v193
	v_add_u32_e32 v194, s98, v160
	ds_read_b32 v194, v194
	v_add_u32_e32 v195, s98, v161
	ds_read_b32 v195, v195
	v_add_u32_e32 v196, s98, v162
	ds_read_b32 v196, v196
	v_add_u32_e32 v197, s98, v163
	ds_read_b32 v197, v197
	v_add_u32_e32 v198, s98, v164
	ds_read_b32 v198, v198
	v_add_u32_e32 v199, s98, v165
	ds_read_b32 v199, v199
	v_add_u32_e32 v202, s98, v166
	ds_read_b32 v202, v202
	s_waitcnt lgkmcnt(11)
	v_add_f32_e32 v189, v2, v189
	v_cndmask_b32_e64 v0, v203, v189, s[2:3]
	v_add_u32_e32 v189, s98, v167
	ds_read_b32 v189, v189
	s_waitcnt lgkmcnt(11)
	v_add_f32_e32 v190, v3, v190
	v_cndmask_b32_e64 v1, v203, v190, s[48:49]
	v_add_u32_e32 v190, s98, v168
	ds_read_b32 v190, v190
	s_waitcnt lgkmcnt(11)
	v_add_f32_e32 v191, v4, v191
	v_cndmask_b32_e64 v2, v203, v191, s[52:53]
	v_add_u32_e32 v191, s98, v169
	ds_read_b32 v191, v191
	s_waitcnt lgkmcnt(11)
	v_add_f32_e32 v192, v5, v192
	v_cndmask_b32_e64 v3, v203, v192, s[54:55]
	v_add_u32_e32 v192, s98, v170
	ds_read_b32 v192, v192
	s_waitcnt lgkmcnt(11)
	v_add_f32_e32 v193, v6, v193
	v_cndmask_b32_e64 v4, v203, v193, s[56:57]
	v_add_u32_e32 v193, s98, v171
	ds_read_b32 v193, v193
	s_waitcnt lgkmcnt(11)
	v_add_f32_e32 v194, v7, v194
	v_cndmask_b32_e64 v5, v203, v194, s[58:59]
	v_add_u32_e32 v194, s98, v172
	ds_read_b32 v194, v194
	s_waitcnt lgkmcnt(11)
	v_add_f32_e32 v195, v8, v195
	v_cndmask_b32_e64 v6, v203, v195, s[60:61]
	v_add_u32_e32 v195, s98, v173
	ds_read_b32 v195, v195
	s_waitcnt lgkmcnt(11)
	v_add_f32_e32 v196, v9, v196
	v_cndmask_b32_e64 v7, v203, v196, s[62:63]
	v_add_u32_e32 v196, s98, v174
	ds_read_b32 v196, v196
	s_waitcnt lgkmcnt(11)
	v_add_f32_e32 v197, v10, v197
	v_cndmask_b32_e64 v8, v203, v197, s[64:65]
	v_add_u32_e32 v197, s98, v175
	ds_read_b32 v197, v197
	s_waitcnt lgkmcnt(11)
	v_add_f32_e32 v198, v11, v198
	v_cndmask_b32_e64 v9, v203, v198, s[66:67]
	v_add_u32_e32 v198, s98, v176
	ds_read_b32 v198, v198
	s_waitcnt lgkmcnt(11)
	v_add_f32_e32 v199, v12, v199
	v_cndmask_b32_e64 v10, v203, v199, s[68:69]
	v_add_u32_e32 v199, s98, v177
	ds_read_b32 v199, v199
	s_waitcnt lgkmcnt(11)
	v_add_f32_e32 v202, v13, v202
	v_cndmask_b32_e64 v11, v203, v202, s[70:71]
	v_add_u32_e32 v202, s98, v178
	ds_read_b32 v202, v202
	s_waitcnt lgkmcnt(11)
	v_add_f32_e32 v189, v14, v189
	v_cndmask_b32_e64 v12, v203, v189, s[72:73]
	v_add_u32_e32 v189, s98, v179
	ds_read_b32 v189, v189
	s_waitcnt lgkmcnt(11)
	v_add_f32_e32 v190, v15, v190
	v_cndmask_b32_e64 v13, v203, v190, s[74:75]
	v_add_u32_e32 v190, s98, v180
	ds_read_b32 v190, v190
	s_waitcnt lgkmcnt(11)
	v_add_f32_e32 v191, v16, v191
	v_cndmask_b32_e64 v14, v203, v191, s[76:77]
	v_add_u32_e32 v191, s98, v181
	ds_read_b32 v191, v191
	s_waitcnt lgkmcnt(11)
	v_add_f32_e32 v192, v17, v192
	v_cndmask_b32_e64 v15, v203, v192, s[78:79]
	v_add_u32_e32 v192, s98, v182
	ds_read_b32 v192, v192
	s_waitcnt lgkmcnt(11)
	v_add_f32_e32 v193, v80, v193
	v_cndmask_b32_e64 v16, v203, v193, s[80:81]
	v_add_u32_e32 v193, s98, v183
	ds_read_b32 v193, v193
	s_waitcnt lgkmcnt(11)
	v_add_f32_e32 v194, v81, v194
	v_cndmask_b32_e64 v17, v203, v194, s[82:83]
	v_add_u32_e32 v194, s98, v184
	ds_read_b32 v194, v194
	s_waitcnt lgkmcnt(11)
	v_add_f32_e32 v195, v82, v195
	v_cndmask_b32_e64 v18, v203, v195, s[84:85]
	v_add_u32_e32 v195, s98, v185
	ds_read_b32 v195, v195
	s_waitcnt lgkmcnt(11)
	v_add_f32_e32 v196, v83, v196
	v_cndmask_b32_e64 v19, v203, v196, s[86:87]
	v_add_u32_e32 v196, s98, v186
	ds_read_b32 v196, v196
	s_waitcnt lgkmcnt(11)
	v_add_f32_e32 v197, v84, v197
	v_cndmask_b32_e64 v20, v203, v197, s[88:89]
	s_waitcnt lgkmcnt(10)
	v_add_f32_e32 v198, v85, v198
	v_cndmask_b32_e64 v21, v203, v198, s[90:91]
	s_waitcnt lgkmcnt(9)
	v_add_f32_e32 v199, v86, v199
	v_cndmask_b32_e64 v22, v203, v199, s[92:93]
	s_waitcnt lgkmcnt(8)
	v_add_f32_e32 v202, v87, v202
	v_cndmask_b32_e64 v23, v203, v202, s[94:95]
	s_waitcnt lgkmcnt(7)
	v_add_f32_e32 v189, v88, v189
	v_cndmask_b32_e64 v24, v203, v189, s[96:97]
	s_waitcnt lgkmcnt(6)
	v_add_f32_e32 v190, v89, v190
	v_cndmask_b32_e64 v25, v203, v190, s[40:41]
	s_waitcnt lgkmcnt(5)
	v_add_f32_e32 v191, v90, v191
	v_cndmask_b32_e64 v26, v203, v191, s[38:39]
	s_waitcnt lgkmcnt(4)
	v_add_f32_e32 v192, v91, v192
	v_cndmask_b32_e64 v27, v203, v192, s[44:45]
	s_waitcnt lgkmcnt(3)
	v_add_f32_e32 v193, v92, v193
	v_cndmask_b32_e64 v28, v203, v193, s[4:5]
	s_waitcnt lgkmcnt(2)
	v_add_f32_e32 v194, v93, v194
	v_cndmask_b32_e64 v29, v203, v194, s[42:43]
	s_waitcnt lgkmcnt(1)
	v_add_f32_e32 v195, v94, v195
	v_cndmask_b32_e64 v30, v203, v195, s[50:51]
	s_waitcnt lgkmcnt(0)
	v_add_f32_e32 v196, v95, v196
	v_cndmask_b32_e64 v31, v203, v196, s[6:7]

.LBB0_353:
	v_add_u32_e32 v30, s98, v185
	ds_read_b32 v30, v30
	s_waitcnt lgkmcnt(0)
	v_add_f32_e32 v30, v94, v30
	s_or_b64 exec, exec, vcc
	s_and_saveexec_b64 vcc, s[6:7]
	s_cbranch_execz .LBB0_348
.LBB0_354:
	v_add_u32_e32 v31, s98, v186
	ds_read_b32 v31, v31
	s_waitcnt lgkmcnt(0)
	v_add_f32_e32 v31, v95, v31
	s_or_b64 exec, exec, vcc
	s_cmp_lg_u32 s16, 0
	s_cbranch_scc1 .LBB0_349
